# m1 gate-statistics serial loop: LDS reads batched 16 steps per trip (was 8)
# speedup vs baseline: 1.0045x; 1.0045x over previous
.LBB0_475:
	v_mov_b32_e32 v3, s11
	ds_read_b32 v10, v3
	ds_read_b32 v11, v3 offset:512
	ds_read_b32 v12, v3 offset:4
	ds_read_b32 v13, v3 offset:516
	ds_read_b32 v14, v3 offset:8
	ds_read_b32 v15, v3 offset:520
	ds_read_b32 v16, v3 offset:12
	ds_read_b32 v17, v3 offset:524
	ds_read_b32 v18, v3 offset:16
	ds_read_b32 v19, v3 offset:528
	ds_read_b32 v20, v3 offset:20
	ds_read_b32 v21, v3 offset:532
	ds_read_b32 v22, v3 offset:24
	ds_read_b32 v23, v3 offset:536
	ds_read_b32 v24, v3 offset:28
	ds_read_b32 v25, v3 offset:540
	ds_read_b32 v26, v3 offset:32
	ds_read_b32 v27, v3 offset:544
	ds_read_b32 v28, v3 offset:36
	ds_read_b32 v29, v3 offset:548
	ds_read_b32 v30, v3 offset:40
	ds_read_b32 v31, v3 offset:552
	ds_read_b32 v32, v3 offset:44
	ds_read_b32 v33, v3 offset:556
	ds_read_b32 v34, v3 offset:48
	ds_read_b32 v35, v3 offset:560
	ds_read_b32 v36, v3 offset:52
	ds_read_b32 v37, v3 offset:564
	ds_read_b32 v38, v3 offset:56
	ds_read_b32 v39, v3 offset:568
	ds_read_b32 v40, v3 offset:60
	ds_read_b32 v41, v3 offset:572
	s_waitcnt lgkmcnt(0)
	s_add_u32 s12, s3, s4
	s_addc_u32 s13, s10, s5
	global_store_dword v1, v2, s[12:13]
	s_add_u32 s12, s8, s4
	v_add_f32_e32 v2, v2, v10
	v_add_f32_e32 v3, v10, v11
	v_max_f32_e32 v3, v2, v3
	s_addc_u32 s13, s9, s5
	v_sub_f32_e32 v2, v2, v3
	s_add_u32 s14, s6, s4
	v_mul_f32_e32 v2, 0x3fb8aa3b, v2
	s_addc_u32 s15, s7, s5
	v_exp_f32_e32 v4, v2
	s_add_u32 s4, s4, 4
	s_addc_u32 s5, s5, 0
	v_mov_b32_e32 v2, v3
	global_store_dword v1, v3, s[12:13]
	global_store_dword v1, v4, s[14:15]
	s_add_u32 s12, s3, s4
	s_addc_u32 s13, s10, s5
	global_store_dword v1, v2, s[12:13]
	s_add_u32 s12, s8, s4
	v_add_f32_e32 v2, v2, v12
	v_add_f32_e32 v3, v12, v13
	v_max_f32_e32 v3, v2, v3
	s_addc_u32 s13, s9, s5
	v_sub_f32_e32 v2, v2, v3
	s_add_u32 s14, s6, s4
	v_mul_f32_e32 v2, 0x3fb8aa3b, v2
	s_addc_u32 s15, s7, s5
	v_exp_f32_e32 v4, v2
	s_add_u32 s4, s4, 4
	s_addc_u32 s5, s5, 0
	v_mov_b32_e32 v2, v3
	global_store_dword v1, v3, s[12:13]
	global_store_dword v1, v4, s[14:15]
	s_add_u32 s12, s3, s4
	s_addc_u32 s13, s10, s5
	global_store_dword v1, v2, s[12:13]
	s_add_u32 s12, s8, s4
	v_add_f32_e32 v2, v2, v14
	v_add_f32_e32 v3, v14, v15
	v_max_f32_e32 v3, v2, v3
	s_addc_u32 s13, s9, s5
	v_sub_f32_e32 v2, v2, v3
	s_add_u32 s14, s6, s4
	v_mul_f32_e32 v2, 0x3fb8aa3b, v2
	s_addc_u32 s15, s7, s5
	v_exp_f32_e32 v4, v2
	s_add_u32 s4, s4, 4
	s_addc_u32 s5, s5, 0
	v_mov_b32_e32 v2, v3
	global_store_dword v1, v3, s[12:13]
	global_store_dword v1, v4, s[14:15]
	s_add_u32 s12, s3, s4
	s_addc_u32 s13, s10, s5
	global_store_dword v1, v2, s[12:13]
	s_add_u32 s12, s8, s4
	v_add_f32_e32 v2, v2, v16
	v_add_f32_e32 v3, v16, v17
	v_max_f32_e32 v3, v2, v3
	s_addc_u32 s13, s9, s5
	v_sub_f32_e32 v2, v2, v3
	s_add_u32 s14, s6, s4
	v_mul_f32_e32 v2, 0x3fb8aa3b, v2
	s_addc_u32 s15, s7, s5
	v_exp_f32_e32 v4, v2
	s_add_u32 s4, s4, 4
	s_addc_u32 s5, s5, 0
	v_mov_b32_e32 v2, v3
	global_store_dword v1, v3, s[12:13]
	global_store_dword v1, v4, s[14:15]
	s_add_u32 s12, s3, s4
	s_addc_u32 s13, s10, s5
	global_store_dword v1, v2, s[12:13]
	s_add_u32 s12, s8, s4
	v_add_f32_e32 v2, v2, v18
	v_add_f32_e32 v3, v18, v19
	v_max_f32_e32 v3, v2, v3
	s_addc_u32 s13, s9, s5
	v_sub_f32_e32 v2, v2, v3
	s_add_u32 s14, s6, s4
	v_mul_f32_e32 v2, 0x3fb8aa3b, v2
	s_addc_u32 s15, s7, s5
	v_exp_f32_e32 v4, v2
	s_add_u32 s4, s4, 4
	s_addc_u32 s5, s5, 0
	v_mov_b32_e32 v2, v3
	global_store_dword v1, v3, s[12:13]
	global_store_dword v1, v4, s[14:15]
	s_add_u32 s12, s3, s4
	s_addc_u32 s13, s10, s5
	global_store_dword v1, v2, s[12:13]
	s_add_u32 s12, s8, s4
	v_add_f32_e32 v2, v2, v20
	v_add_f32_e32 v3, v20, v21
	v_max_f32_e32 v3, v2, v3
	s_addc_u32 s13, s9, s5
	v_sub_f32_e32 v2, v2, v3
	s_add_u32 s14, s6, s4
	v_mul_f32_e32 v2, 0x3fb8aa3b, v2
	s_addc_u32 s15, s7, s5
	v_exp_f32_e32 v4, v2
	s_add_u32 s4, s4, 4
	s_addc_u32 s5, s5, 0
	v_mov_b32_e32 v2, v3
	global_store_dword v1, v3, s[12:13]
	global_store_dword v1, v4, s[14:15]
	s_add_u32 s12, s3, s4
	s_addc_u32 s13, s10, s5
	global_store_dword v1, v2, s[12:13]
	s_add_u32 s12, s8, s4
	v_add_f32_e32 v2, v2, v22
	v_add_f32_e32 v3, v22, v23
	v_max_f32_e32 v3, v2, v3
	s_addc_u32 s13, s9, s5
	v_sub_f32_e32 v2, v2, v3
	s_add_u32 s14, s6, s4
	v_mul_f32_e32 v2, 0x3fb8aa3b, v2
	s_addc_u32 s15, s7, s5
	v_exp_f32_e32 v4, v2
	s_add_u32 s4, s4, 4
	s_addc_u32 s5, s5, 0
	v_mov_b32_e32 v2, v3
	global_store_dword v1, v3, s[12:13]
	global_store_dword v1, v4, s[14:15]
	s_add_u32 s12, s3, s4
	s_addc_u32 s13, s10, s5
	global_store_dword v1, v2, s[12:13]
	s_add_u32 s12, s8, s4
	v_add_f32_e32 v2, v2, v24
	v_add_f32_e32 v3, v24, v25
	v_max_f32_e32 v3, v2, v3
	s_addc_u32 s13, s9, s5
	v_sub_f32_e32 v2, v2, v3
	s_add_u32 s14, s6, s4
	v_mul_f32_e32 v2, 0x3fb8aa3b, v2
	s_addc_u32 s15, s7, s5
	v_exp_f32_e32 v4, v2
	s_add_u32 s4, s4, 4
	s_addc_u32 s5, s5, 0
	v_mov_b32_e32 v2, v3
	global_store_dword v1, v3, s[12:13]
	global_store_dword v1, v4, s[14:15]
	s_add_u32 s12, s3, s4
	s_addc_u32 s13, s10, s5
	global_store_dword v1, v2, s[12:13]
	s_add_u32 s12, s8, s4
	v_add_f32_e32 v2, v2, v26
	v_add_f32_e32 v3, v26, v27
	v_max_f32_e32 v3, v2, v3
	s_addc_u32 s13, s9, s5
	v_sub_f32_e32 v2, v2, v3
	s_add_u32 s14, s6, s4
	v_mul_f32_e32 v2, 0x3fb8aa3b, v2
	s_addc_u32 s15, s7, s5
	v_exp_f32_e32 v4, v2
	s_add_u32 s4, s4, 4
	s_addc_u32 s5, s5, 0
	v_mov_b32_e32 v2, v3
	global_store_dword v1, v3, s[12:13]
	global_store_dword v1, v4, s[14:15]
	s_add_u32 s12, s3, s4
	s_addc_u32 s13, s10, s5
	global_store_dword v1, v2, s[12:13]
	s_add_u32 s12, s8, s4
	v_add_f32_e32 v2, v2, v28
	v_add_f32_e32 v3, v28, v29
	v_max_f32_e32 v3, v2, v3
	s_addc_u32 s13, s9, s5
	v_sub_f32_e32 v2, v2, v3
	s_add_u32 s14, s6, s4
	v_mul_f32_e32 v2, 0x3fb8aa3b, v2
	s_addc_u32 s15, s7, s5
	v_exp_f32_e32 v4, v2
	s_add_u32 s4, s4, 4
	s_addc_u32 s5, s5, 0
	v_mov_b32_e32 v2, v3
	global_store_dword v1, v3, s[12:13]
	global_store_dword v1, v4, s[14:15]
	s_add_u32 s12, s3, s4
	s_addc_u32 s13, s10, s5
	global_store_dword v1, v2, s[12:13]
	s_add_u32 s12, s8, s4
	v_add_f32_e32 v2, v2, v30
	v_add_f32_e32 v3, v30, v31
	v_max_f32_e32 v3, v2, v3
	s_addc_u32 s13, s9, s5
	v_sub_f32_e32 v2, v2, v3
	s_add_u32 s14, s6, s4
	v_mul_f32_e32 v2, 0x3fb8aa3b, v2
	s_addc_u32 s15, s7, s5
	v_exp_f32_e32 v4, v2
	s_add_u32 s4, s4, 4
	s_addc_u32 s5, s5, 0
	v_mov_b32_e32 v2, v3
	global_store_dword v1, v3, s[12:13]
	global_store_dword v1, v4, s[14:15]
	s_add_u32 s12, s3, s4
	s_addc_u32 s13, s10, s5
	global_store_dword v1, v2, s[12:13]
	s_add_u32 s12, s8, s4
	v_add_f32_e32 v2, v2, v32
	v_add_f32_e32 v3, v32, v33
	v_max_f32_e32 v3, v2, v3
	s_addc_u32 s13, s9, s5
	v_sub_f32_e32 v2, v2, v3
	s_add_u32 s14, s6, s4
	v_mul_f32_e32 v2, 0x3fb8aa3b, v2
	s_addc_u32 s15, s7, s5
	v_exp_f32_e32 v4, v2
	s_add_u32 s4, s4, 4
	s_addc_u32 s5, s5, 0
	v_mov_b32_e32 v2, v3
	global_store_dword v1, v3, s[12:13]
	global_store_dword v1, v4, s[14:15]
	s_add_u32 s12, s3, s4
	s_addc_u32 s13, s10, s5
	global_store_dword v1, v2, s[12:13]
	s_add_u32 s12, s8, s4
	v_add_f32_e32 v2, v2, v34
	v_add_f32_e32 v3, v34, v35
	v_max_f32_e32 v3, v2, v3
	s_addc_u32 s13, s9, s5
	v_sub_f32_e32 v2, v2, v3
	s_add_u32 s14, s6, s4
	v_mul_f32_e32 v2, 0x3fb8aa3b, v2
	s_addc_u32 s15, s7, s5
	v_exp_f32_e32 v4, v2
	s_add_u32 s4, s4, 4
	s_addc_u32 s5, s5, 0
	v_mov_b32_e32 v2, v3
	global_store_dword v1, v3, s[12:13]
	global_store_dword v1, v4, s[14:15]
	s_add_u32 s12, s3, s4
	s_addc_u32 s13, s10, s5
	global_store_dword v1, v2, s[12:13]
	s_add_u32 s12, s8, s4
	v_add_f32_e32 v2, v2, v36
	v_add_f32_e32 v3, v36, v37
	v_max_f32_e32 v3, v2, v3
	s_addc_u32 s13, s9, s5
	v_sub_f32_e32 v2, v2, v3
	s_add_u32 s14, s6, s4
	v_mul_f32_e32 v2, 0x3fb8aa3b, v2
	s_addc_u32 s15, s7, s5
	v_exp_f32_e32 v4, v2
	s_add_u32 s4, s4, 4
	s_addc_u32 s5, s5, 0
	v_mov_b32_e32 v2, v3
	global_store_dword v1, v3, s[12:13]
	global_store_dword v1, v4, s[14:15]
	s_add_u32 s12, s3, s4
	s_addc_u32 s13, s10, s5
	global_store_dword v1, v2, s[12:13]
	s_add_u32 s12, s8, s4
	v_add_f32_e32 v2, v2, v38
	v_add_f32_e32 v3, v38, v39
	v_max_f32_e32 v3, v2, v3
	s_addc_u32 s13, s9, s5
	v_sub_f32_e32 v2, v2, v3
	s_add_u32 s14, s6, s4
	v_mul_f32_e32 v2, 0x3fb8aa3b, v2
	s_addc_u32 s15, s7, s5
	v_exp_f32_e32 v4, v2
	s_add_u32 s4, s4, 4
	s_addc_u32 s5, s5, 0
	v_mov_b32_e32 v2, v3
	global_store_dword v1, v3, s[12:13]
	global_store_dword v1, v4, s[14:15]
	s_add_u32 s12, s3, s4
	s_addc_u32 s13, s10, s5
	global_store_dword v1, v2, s[12:13]
	s_add_u32 s12, s8, s4
	v_add_f32_e32 v2, v2, v40
	v_add_f32_e32 v3, v40, v41
	v_max_f32_e32 v3, v2, v3
	s_addc_u32 s13, s9, s5
	v_sub_f32_e32 v2, v2, v3
	s_add_u32 s14, s6, s4
	v_mul_f32_e32 v2, 0x3fb8aa3b, v2
	s_addc_u32 s15, s7, s5
	v_exp_f32_e32 v4, v2
	s_add_u32 s4, s4, 4
	s_addc_u32 s5, s5, 0
	v_mov_b32_e32 v2, v3
	global_store_dword v1, v3, s[12:13]
	global_store_dword v1, v4, s[14:15]
	s_add_i32 s11, s11, 64
	s_cmpk_lg_i32 s4, 0x200
	s_cbranch_scc1 .LBB0_475
